# v038 + NA: removed 33 dead loop-carried exp-result copies in the PV sections
# baseline (speedup 1.0000x reference)
.LBB0_818:
	v_exp_f32_e32 v16, v16
	v_exp_f32_e32 v80, v80
	v_exp_f32_e32 v0, v17
	v_exp_f32_e32 v188, v95
	v_exp_f32_e32 v18, v18
	v_add_f32_e32 v189, v80, v16
	v_exp_f32_e32 v82, v82
	v_pk_add_f32 v[130:131], v[188:189], v[0:1]
	v_exp_f32_e32 v192, v81
	v_pk_add_f32 v[190:191], v[130:131], v[130:131] op_sel_hi:[0,1]
	v_exp_f32_e32 v190, v19
	v_add_f32_e32 v193, v82, v18
	v_exp_f32_e32 v20, v20
	v_exp_f32_e32 v84, v84
	v_pk_add_f32 v[130:131], v[192:193], v[190:191]
	v_exp_f32_e32 v196, v89
	v_pk_add_f32 v[194:195], v[130:131], v[130:131] op_sel_hi:[0,1]
	v_exp_f32_e32 v194, v21
	v_add_f32_e32 v197, v84, v20
	v_exp_f32_e32 v22, v22
	v_exp_f32_e32 v86, v86
	v_pk_add_f32 v[130:131], v[196:197], v[194:195]
	v_exp_f32_e32 v200, v83
	v_pk_add_f32 v[198:199], v[130:131], v[130:131] op_sel_hi:[0,1]
	v_exp_f32_e32 v198, v23
	v_add_f32_e32 v201, v86, v22
	v_exp_f32_e32 v24, v24
	v_exp_f32_e32 v88, v88
	v_pk_add_f32 v[130:131], v[200:201], v[198:199]
	v_exp_f32_e32 v204, v91
	v_pk_add_f32 v[202:203], v[130:131], v[130:131] op_sel_hi:[0,1]
	v_exp_f32_e32 v202, v25
	v_add_f32_e32 v205, v88, v24
	v_exp_f32_e32 v26, v26
	v_exp_f32_e32 v90, v90
	v_pk_add_f32 v[130:131], v[204:205], v[202:203]
	v_exp_f32_e32 v210, v85
	v_pk_add_f32 v[208:209], v[130:131], v[130:131] op_sel_hi:[0,1]
	v_exp_f32_e32 v208, v27
	v_add_f32_e32 v211, v90, v26
	v_exp_f32_e32 v60, v60
	v_exp_f32_e32 v92, v92
	v_pk_add_f32 v[130:131], v[210:211], v[208:209]
	v_exp_f32_e32 v214, v93
	v_pk_add_f32 v[212:213], v[130:131], v[130:131] op_sel_hi:[0,1]
	v_exp_f32_e32 v212, v61
	v_add_f32_e32 v215, v92, v60
	s_and_b32 s72, s87, 2
	s_mulk_i32 s72, 0x2400
	v_pk_add_f32 v[130:131], v[214:215], v[212:213]
	v_add_u32_e32 v17, s72, v173
	v_pk_add_f32 v[216:217], v[130:131], v[130:131] op_sel_hi:[0,1]
	v_exp_f32_e32 v216, v63
	v_exp_f32_e32 v218, v87
	v_exp_f32_e32 v62, v62
	v_exp_f32_e32 v94, v94
	v_cvt_pk_bf16_f32 v130, v16, v0
	v_cvt_pk_bf16_f32 v131, v18, v190
	v_cvt_pk_bf16_f32 v132, v20, v194
	v_cvt_pk_bf16_f32 v133, v22, v198
	v_cvt_pk_bf16_f32 v134, v24, v202
	v_cvt_pk_bf16_f32 v135, v26, v208
	v_cvt_pk_bf16_f32 v136, v60, v212
	v_cvt_pk_bf16_f32 v137, v62, v216
	v_cvt_pk_bf16_f32 v138, v80, v188
	v_cvt_pk_bf16_f32 v139, v82, v192
	v_cvt_pk_bf16_f32 v140, v84, v196
	v_cvt_pk_bf16_f32 v141, v86, v200
	v_cvt_pk_bf16_f32 v142, v88, v204
	v_cvt_pk_bf16_f32 v143, v90, v210
	v_cvt_pk_bf16_f32 v144, v92, v214
	v_cvt_pk_bf16_f32 v145, v94, v218
	ds_read_b128 v[184:187], v17 offset:53248
	ds_read_b128 v[220:223], v17 offset:57856
	ds_read_b128 v[224:227], v17 offset:53280
	ds_read_b128 v[228:231], v17 offset:57888
	ds_read_b128 v[232:235], v17 offset:53312
	ds_read_b128 v[236:239], v17 offset:57920
	ds_read_b128 v[240:243], v17 offset:53344
	s_waitcnt lgkmcnt(6)
	v_mfma_f32_32x32x16_bf16 v[44:59], v[184:187], v[130:133], v[44:59]
	v_add_f32_e32 v219, v94, v62
	s_waitcnt lgkmcnt(5)
	v_mfma_f32_32x32x16_bf16 v[28:43], v[220:223], v[130:133], v[28:43]
	ds_read_b128 v[130:133], v17 offset:57952
	s_waitcnt lgkmcnt(5)
	v_mfma_f32_32x32x16_bf16 v[44:59], v[224:227], v[134:137], v[44:59]
	s_waitcnt lgkmcnt(4)
	v_mfma_f32_32x32x16_bf16 v[28:43], v[228:231], v[134:137], v[28:43]
	s_waitcnt lgkmcnt(3)
	v_mfma_f32_32x32x16_bf16 v[44:59], v[232:235], v[138:141], v[44:59]
	s_waitcnt lgkmcnt(2)
	v_mfma_f32_32x32x16_bf16 v[28:43], v[236:239], v[138:141], v[28:43]
	s_waitcnt lgkmcnt(1)
	v_mfma_f32_32x32x16_bf16 v[44:59], v[240:243], v[142:145], v[44:59]
	s_waitcnt lgkmcnt(0)
	v_mfma_f32_32x32x16_bf16 v[28:43], v[130:133], v[142:145], v[28:43]
	v_add_f32_e64 v130, v218, v216
	v_add_f32_e64 v131, v219, v217
	v_add_f32_e32 v17, v130, v131
	v_add_f32_e32 v178, v178, v17
	s_andn2_b64 vcc, exec, s[96:97]
	s_cbranch_vccnz .LBB0_767
.LBB0_819:
.LBB0_823:
	s_andn2_b64 s[72:73], exec, s[94:95]
	s_andn2_b64 vcc, exec, s[94:95]
	s_cbranch_vccnz .LBB0_829
	s_mov_b64 s[94:95], -1
	s_cmp_eq_u32 s89, 3
	s_cbranch_scc1 .LBB0_827
	v_cmp_lt_f32_e32 vcc, s3, v3
	s_cbranch_vccz .LBB0_866
	v_max_f32_e32 v0, v3, v3
	v_max_f32_e32 v0, 0, v0

.LBB0_863:
	s_and_b64 vcc, exec, s[72:73]
	s_cbranch_vccnz .LBB0_865
	v_exp_f32_e32 v64, v64
	v_exp_f32_e32 v96, v96
	v_exp_f32_e32 v136, v65
	v_exp_f32_e32 v0, v97
	v_exp_f32_e32 v66, v66
	v_add_f32_e32 v137, v64, v96
	v_exp_f32_e32 v98, v98
	v_pk_add_f32 v[4:5], v[136:137], v[0:1]
	v_exp_f32_e32 v140, v67
	v_pk_add_f32 v[138:139], v[4:5], v[4:5] op_sel_hi:[0,1]
	v_exp_f32_e32 v138, v99
	v_add_f32_e32 v141, v66, v98
	v_exp_f32_e32 v68, v68
	v_exp_f32_e32 v100, v100
	v_pk_add_f32 v[4:5], v[140:141], v[138:139]
	v_exp_f32_e32 v144, v69
	v_pk_add_f32 v[142:143], v[4:5], v[4:5] op_sel_hi:[0,1]
	v_exp_f32_e32 v142, v101
	v_add_f32_e32 v145, v68, v100
	v_exp_f32_e32 v70, v70
	v_exp_f32_e32 v102, v102
	v_pk_add_f32 v[4:5], v[144:145], v[142:143]
	v_exp_f32_e32 v184, v71
	v_pk_add_f32 v[182:183], v[4:5], v[4:5] op_sel_hi:[0,1]
	v_exp_f32_e32 v182, v103
	v_add_f32_e32 v185, v70, v102
	v_exp_f32_e32 v72, v72
	v_exp_f32_e32 v104, v104
	v_pk_add_f32 v[4:5], v[184:185], v[182:183]
	v_exp_f32_e32 v188, v73
	v_pk_add_f32 v[186:187], v[4:5], v[4:5] op_sel_hi:[0,1]
	v_exp_f32_e32 v186, v105
	v_add_f32_e32 v189, v72, v104
	v_exp_f32_e32 v74, v74
	v_exp_f32_e32 v106, v106
	v_pk_add_f32 v[4:5], v[188:189], v[186:187]
	v_exp_f32_e32 v192, v75
	v_pk_add_f32 v[190:191], v[4:5], v[4:5] op_sel_hi:[0,1]
	v_exp_f32_e32 v190, v107
	v_add_f32_e32 v193, v74, v106
	v_exp_f32_e32 v76, v76
	v_exp_f32_e32 v108, v108
	v_pk_add_f32 v[4:5], v[192:193], v[190:191]
	v_exp_f32_e32 v196, v77
	v_pk_add_f32 v[194:195], v[4:5], v[4:5] op_sel_hi:[0,1]
	v_exp_f32_e32 v194, v109
	v_add_f32_e32 v197, v76, v108
	s_and_b32 s0, s0, 3
	s_mulk_i32 s0, 0x2400
	v_pk_add_f32 v[4:5], v[196:197], v[194:195]
	v_add_u32_e32 v65, s0, v173
	v_pk_add_f32 v[198:199], v[4:5], v[4:5] op_sel_hi:[0,1]
	v_exp_f32_e32 v78, v78
	v_exp_f32_e32 v110, v110
	v_exp_f32_e32 v200, v79
	v_exp_f32_e32 v198, v111
	v_cvt_pk_bf16_f32 v4, v64, v136
	v_cvt_pk_bf16_f32 v5, v66, v140
	v_cvt_pk_bf16_f32 v6, v68, v144
	v_cvt_pk_bf16_f32 v7, v70, v184
	v_cvt_pk_bf16_f32 v8, v72, v188
	v_cvt_pk_bf16_f32 v9, v74, v192
	v_cvt_pk_bf16_f32 v10, v76, v196
	v_cvt_pk_bf16_f32 v11, v78, v200
	v_cvt_pk_bf16_f32 v12, v96, v0
	v_cvt_pk_bf16_f32 v13, v98, v138
	v_cvt_pk_bf16_f32 v14, v100, v142
	v_cvt_pk_bf16_f32 v15, v102, v182
	v_cvt_pk_bf16_f32 v128, v104, v186
	v_cvt_pk_bf16_f32 v129, v106, v190
	v_cvt_pk_bf16_f32 v130, v108, v194
	v_cvt_pk_bf16_f32 v131, v110, v198
	ds_read_b128 v[132:135], v65 offset:53248
	ds_read_b128 v[220:223], v65 offset:57856
	ds_read_b128 v[224:227], v65 offset:53280
	ds_read_b128 v[228:231], v65 offset:57888
	ds_read_b128 v[232:235], v65 offset:53312
	ds_read_b128 v[236:239], v65 offset:57920
	ds_read_b128 v[240:243], v65 offset:53344
	s_waitcnt lgkmcnt(6)
	v_mfma_f32_32x32x16_bf16 v[44:59], v[132:135], v[4:7], v[44:59]
	v_add_f32_e32 v201, v78, v110
	s_waitcnt lgkmcnt(5)
	v_mfma_f32_32x32x16_bf16 v[28:43], v[220:223], v[4:7], v[28:43]
	ds_read_b128 v[4:7], v65 offset:57952
	s_waitcnt lgkmcnt(5)
	v_mfma_f32_32x32x16_bf16 v[44:59], v[224:227], v[8:11], v[44:59]
	s_waitcnt lgkmcnt(4)
	v_mfma_f32_32x32x16_bf16 v[28:43], v[228:231], v[8:11], v[28:43]
	v_add_f32_e64 v8, v200, v198
	v_add_f32_e64 v9, v201, v199
	v_add_f32_e32 v8, v8, v9
	v_add_f32_e32 v178, v178, v8
	s_waitcnt lgkmcnt(3)
	v_mfma_f32_32x32x16_bf16 v[44:59], v[232:235], v[12:15], v[44:59]
	s_waitcnt lgkmcnt(2)
	v_mfma_f32_32x32x16_bf16 v[28:43], v[236:239], v[12:15], v[28:43]
	s_waitcnt lgkmcnt(1)
	v_mfma_f32_32x32x16_bf16 v[44:59], v[240:243], v[128:131], v[44:59]
	s_waitcnt lgkmcnt(0)
	v_mfma_f32_32x32x16_bf16 v[28:43], v[4:7], v[128:131], v[28:43]
